# as v38 plus MLA loop: waves 0-3 (critical S-softmax-PV half) stay at s_setprio 1 through the whole tile instead of only during S
# speedup vs baseline: 1.0017x; 1.0009x over previous
; #define LAS __attribute__((address_space(3)))
; __device__ __forceinline__ int crow(int r, int hi) { return (r & 3) + 8 * (r >> 2) + 4 * hi; }
; __device__ __forceinline__ float halfmax(float m) { auto rr = __builtin_amdgcn_permlane32_swap(__float_as_uint(m), __float_as_uint(m), false, false); return fmaxf(__uint_as_float(rr[0]), __uint_as_float(rr[1])); }
; #define MX3(a_, b_, c_) __builtin_fmaxf(__builtin_fmaxf((a_), (b_)), (c_))
; template <int MODE> __device__ __forceinline__ void attn_unit(const Unit& a, char* shm) {
;     ...
;             for (int d0 = 0; d0 < ND; ++d0) {
;                 const bf16x8 b0 = *(const LAS bf16x8*)(kp + d0 * 2048), b1 = *(const LAS bf16x8*)(kp + d0 * 2048 + 512);
;                 p0 = __builtin_amdgcn_mfma_f32_32x32x16_bf16(b0, qr[d0], p0, 0, 0, 0);
;                 p1 = __builtin_amdgcn_mfma_f32_32x32x16_bf16(b1, qr[d0], p1, 0, 0, 0);
;             }
;             if (MODE == 1) {
; #pragma unroll
;                 for (int r = 0; r < 16; ++r) { const int ks = 64 * t + crow(r, hi); const int r0 = abs(tq - ks), r1 = abs(tq - ks - 32);
;                     p0[r] = (r0 <= 128) ? p0[r] - a.slope2 * (float)r0 : -INFINITY; p1[r] = (r1 <= 128) ? p1[r] - a.slope2 * (float)r1 : -INFINITY; }
;             }
;     ...
;             float ra = MX3(p0[0], p0[1], p1[0]), rb = MX3(p0[2], p0[3], p1[1]); ra = MX3(ra, p1[2], p1[3]);
; #pragma unroll
;             for (int r = 4; r < 16; r += 4) { ra = MX3(ra, p0[r], p0[r + 1]); rb = MX3(rb, p0[r + 2], p0[r + 3]); ra = MX3(ra, p1[r], p1[r + 1]); rb = MX3(rb, p1[r + 2], p1[r + 3]); }
;     ...
;             float rm = halfmax(__builtin_fmaxf(ra, rb));
;             const bool first = (MODE == 0) && (t == a.t_lo);
;             if (first || __any(rm > THR)) {
;                 const float dl = first ? rm : fmaxf(rm, 0.f);
;                 mhat += dl;
; #pragma unroll
;                 for (int r = 0; r < 16; ++r) { p0[r] -= dl; p1[r] -= dl; negm[r] = -mhat; }
;                 if (!first) {
;                     const float f = __builtin_amdgcn_exp2f(-dl); l_reg *= f;
;                     if (hi == 0) wsf[r32] = f;
; #pragma unroll
;                     for (int r = 0; r < 16; ++r) { const float fr_ = wsf[crow(r, hi)]; o[0][r] *= fr_; o[1][r] *= fr_; }
;                 }
.Lmla_nokpe:
	s_waitcnt lgkmcnt(9)
	v_mfma_f32_32x32x16_bf16 v[48:63], v[190:193], v[86:89], v[48:63]
	s_lshl_b32 s0, s35, 13
	s_add_i32 s1, s0, s48
	s_mov_b32 m0, s1
	s_nop 0
	global_load_lds_dwordx4 v[106:107], off
	s_mov_b32 m0, s12
	s_waitcnt lgkmcnt(8)
	v_mfma_f32_32x32x16_bf16 v[64:79], v[194:197], v[86:89], v[64:79]
	s_waitcnt lgkmcnt(7)
	v_mfma_f32_32x32x16_bf16 v[48:63], v[198:201], v[90:93], v[48:63]
	s_waitcnt lgkmcnt(6)
	v_mfma_f32_32x32x16_bf16 v[64:79], v[202:205], v[90:93], v[64:79]
	s_waitcnt lgkmcnt(5)
	v_mfma_f32_32x32x16_bf16 v[48:63], v[206:209], v[94:97], v[48:63]
	s_waitcnt lgkmcnt(4)
	v_mfma_f32_32x32x16_bf16 v[64:79], v[210:213], v[94:97], v[64:79]
	s_waitcnt lgkmcnt(3)
	v_mfma_f32_32x32x16_bf16 v[48:63], v[214:217], v[98:101], v[48:63]
	s_waitcnt lgkmcnt(2)
	v_mfma_f32_32x32x16_bf16 v[64:79], v[218:221], v[98:101], v[64:79]
	s_waitcnt lgkmcnt(1)
	v_mfma_f32_32x32x16_bf16 v[48:63], v[222:225], v[102:105], v[48:63]
	s_waitcnt lgkmcnt(0)
	v_mfma_f32_32x32x16_bf16 v[64:79], v[226:229], v[102:105], v[64:79]
	ds_read_b64_tr_b16 v[230:231], v149 offset:24576
	ds_read_b64_tr_b16 v[232:233], v149 offset:25088
	ds_read_b64_tr_b16 v[234:235], v149 offset:25600
	ds_read_b64_tr_b16 v[236:237], v149 offset:26112
	ds_read_b64_tr_b16 v[238:239], v149 offset:26624
	ds_read_b64_tr_b16 v[240:241], v149 offset:27136
	ds_read_b64_tr_b16 v[242:243], v149 offset:27648
	ds_read_b64_tr_b16 v[244:245], v149 offset:28160
	ds_read_b64_tr_b16 v[246:247], v149 offset:28672
	ds_read_b64_tr_b16 v[248:249], v149 offset:29184
	ds_read_b64_tr_b16 v[150:151], v149 offset:29696
	ds_read_b64_tr_b16 v[152:153], v149 offset:30208
	ds_read_b64_tr_b16 v[154:155], v149 offset:30720
	ds_read_b64_tr_b16 v[156:157], v149 offset:31232
	v_max_f32_e32 v118, v49, v49
	v_max_f32_e32 v119, v48, v48
	v_max_f32_e32 v118, v119, v118
	v_max3_f32 v114, v50, v51, v65
	v_max3_f32 v115, v118, v64, v66
	v_max3_f32 v115, v115, v67, v52
	v_max3_f32 v114, v114, v54, v55
	v_max3_f32 v115, v115, v53, v68
	v_max3_f32 v114, v114, v70, v71
	v_max3_f32 v115, v115, v69, v56
	v_max3_f32 v114, v114, v58, v59
	v_max3_f32 v115, v115, v57, v72
	v_max3_f32 v114, v114, v74, v75
	v_max3_f32 v115, v115, v73, v60
	v_max3_f32 v114, v114, v62, v63
	v_max3_f32 v115, v115, v61, v76
	v_max3_f32 v114, v114, v78, v79
	v_max3_f32 v114, v115, v77, v114
	v_mov_b32_e32 v115, v114
	s_nop 1
	v_permlane32_swap_b32_e32 v114, v115
	v_max_f32_e32 v115, v115, v115
	v_max_f32_e32 v114, v114, v114
	v_max_f32_e32 v114, v114, v115
	v_cmp_lt_f32_e32 vcc, s19, v114
	s_cbranch_vccz .LBB0_1920
	s_waitcnt lgkmcnt(0)
	v_max_f32_e32 v32, v114, v114
	v_max_f32_e32 v32, 0, v32
	v_exp_f32_e64 v33, -v32
	s_and_saveexec_b64 s[46:47], s[42:43]
	ds_write_b32 v148, v33 offset:49152
	s_or_b64 exec, exec, s[46:47]
	v_pk_add_f32 v[114:115], v[112:113], v[32:33]
	v_pk_mul_f32 v[40:41], v[112:113], v[32:33]
	v_add_u32_e32 v44, s49, v80
	v_pk_add_f32 v[48:49], v[48:49], v[32:33] op_sel_hi:[1,0] neg_lo:[0,1] neg_hi:[0,1]
	v_pk_add_f32 v[64:65], v[64:65], v[32:33] op_sel_hi:[1,0] neg_lo:[0,1] neg_hi:[0,1]
	v_pk_add_f32 v[50:51], v[50:51], v[32:33] op_sel_hi:[1,0] neg_lo:[0,1] neg_hi:[0,1]
	v_pk_add_f32 v[66:67], v[66:67], v[32:33] op_sel_hi:[1,0] neg_lo:[0,1] neg_hi:[0,1]
	v_pk_add_f32 v[52:53], v[52:53], v[32:33] op_sel_hi:[1,0] neg_lo:[0,1] neg_hi:[0,1]
	v_pk_add_f32 v[68:69], v[68:69], v[32:33] op_sel_hi:[1,0] neg_lo:[0,1] neg_hi:[0,1]
	v_pk_add_f32 v[54:55], v[54:55], v[32:33] op_sel_hi:[1,0] neg_lo:[0,1] neg_hi:[0,1]
	v_pk_add_f32 v[70:71], v[70:71], v[32:33] op_sel_hi:[1,0] neg_lo:[0,1] neg_hi:[0,1]
	v_pk_add_f32 v[56:57], v[56:57], v[32:33] op_sel_hi:[1,0] neg_lo:[0,1] neg_hi:[0,1]
	v_pk_add_f32 v[72:73], v[72:73], v[32:33] op_sel_hi:[1,0] neg_lo:[0,1] neg_hi:[0,1]
	v_pk_add_f32 v[58:59], v[58:59], v[32:33] op_sel_hi:[1,0] neg_lo:[0,1] neg_hi:[0,1]
	v_pk_add_f32 v[74:75], v[74:75], v[32:33] op_sel_hi:[1,0] neg_lo:[0,1] neg_hi:[0,1]
	v_pk_add_f32 v[60:61], v[60:61], v[32:33] op_sel_hi:[1,0] neg_lo:[0,1] neg_hi:[0,1]
	v_pk_add_f32 v[76:77], v[76:77], v[32:33] op_sel_hi:[1,0] neg_lo:[0,1] neg_hi:[0,1]
	v_pk_add_f32 v[62:63], v[62:63], v[32:33] op_sel_hi:[1,0] neg_lo:[0,1] neg_hi:[0,1]
	v_pk_add_f32 v[78:79], v[78:79], v[32:33] op_sel_hi:[1,0] neg_lo:[0,1] neg_hi:[0,1]
	ds_read_b128 v[32:35], v44 offset:49216
	ds_read_b128 v[36:39], v44 offset:49248
	v_mov_b32_e32 v115, v41
	ds_read_b128 v[40:43], v44 offset:49152
	ds_read_b128 v[116:119], v44 offset:49184
	v_pk_add_f32 v[46:47], v[114:115], 0 neg_lo:[1,1] neg_hi:[1,1]
	s_waitcnt lgkmcnt(3)
	v_pk_mul_f32 v[26:27], v[26:27], v[34:35]
	s_waitcnt lgkmcnt(2)
	v_pk_mul_f32 v[30:31], v[30:31], v[38:39]
	v_pk_mul_f32 v[28:29], v[28:29], v[36:37]
	v_pk_mul_f32 v[24:25], v[24:25], v[32:33]
	s_waitcnt lgkmcnt(0)
	v_pk_mul_f32 v[22:23], v[22:23], v[118:119]
	v_pk_mul_f32 v[20:21], v[20:21], v[116:117]
	v_pk_mul_f32 v[18:19], v[18:19], v[42:43]
	v_pk_mul_f32 v[16:17], v[16:17], v[40:41]
	v_pk_mul_f32 v[14:15], v[14:15], v[38:39]
	v_pk_mul_f32 v[12:13], v[12:13], v[36:37]
	v_pk_mul_f32 v[10:11], v[10:11], v[34:35]
	v_pk_mul_f32 v[8:9], v[8:9], v[32:33]
	v_pk_mul_f32 v[6:7], v[6:7], v[118:119]
	v_pk_mul_f32 v[4:5], v[4:5], v[116:117]
	v_pk_mul_f32 v[2:3], v[2:3], v[42:43]
	v_pk_mul_f32 v[0:1], v[0:1], v[40:41]
	v_mov_b32_e32 v47, v46
	v_mov_b32_e32 v45, v46
	v_mov_b32_e32 v44, v46
	v_mov_b32_e32 v43, v46
	v_mov_b32_e32 v42, v46
	v_mov_b32_e32 v41, v46
	v_mov_b32_e32 v40, v46
	v_mov_b32_e32 v39, v46
	v_mov_b32_e32 v38, v46
	v_mov_b32_e32 v37, v46
	v_mov_b32_e32 v36, v46
	v_mov_b32_e32 v35, v46
	v_mov_b32_e32 v34, v46
	v_mov_b32_e32 v33, v46
	v_mov_b32_e32 v32, v46
	v_mov_b64_e32 v[112:113], v[114:115]

; template <int MODE> __device__ __forceinline__ void attn_unit(const Unit& a, char* shm) {
;     ...
;             if (g == 0) ATT_PV(pw, sv); else pend = true;
.LBB0_1924:
	s_setprio 0
	s_and_b64 vcc, exec, s[2:3]
	s_cbranch_vccz .LBB0_1926
	s_waitcnt lgkmcnt(0)
	v_mfma_f32_32x32x16_bf16 v[0:15], v[60:63], v[230:233], v[0:15]
	v_mfma_f32_32x32x16_bf16 v[0:15], v[56:59], v[234:237], v[0:15]
	v_mfma_f32_32x32x16_bf16 v[0:15], v[52:55], v[238:241], v[0:15]
	v_mfma_f32_32x32x16_bf16 v[0:15], v[48:51], v[242:245], v[0:15]
	v_mfma_f32_32x32x16_bf16 v[16:31], v[60:63], v[246:249], v[16:31]
	v_mfma_f32_32x32x16_bf16 v[16:31], v[56:59], v[150:153], v[16:31]
	v_mfma_f32_32x32x16_bf16 v[16:31], v[52:55], v[154:157], v[16:31]
	v_mfma_f32_32x32x16_bf16 v[16:31], v[48:51], v[158:161], v[16:31]
